# deferred layer-1 weight conversion, smaller share: only prep tiles >= 2624 moved into the phase-1 tail
# speedup vs baseline: 1.0019x; 1.0019x over previous
;   DI unsigned* bar() const { return (unsigned*)(ws + OFF_BAR); }
; #define LAS __attribute__((address_space(3)))
; __device__ __forceinline__ unsigned xb_add(unsigned* p, unsigned v) { return __hip_atomic_fetch_add(p, v, __ATOMIC_RELAXED, __HIP_MEMORY_SCOPE_AGENT); }
; __device__ __forceinline__ unsigned xb_xcc_id() { return (unsigned)__builtin_amdgcn_s_getreg((3 << 11) | 20) & 0xFu; }
; __device__ __forceinline__ XcdBarrier xcd_barrier_post(unsigned* bar, volatile LAS unsigned* st) {
;     XcdBarrier b; b.bar = bar; b.x = xb_xcc_id(); b.st = st;
;     if (threadIdx.x == 0) (void)xb_add(&bar[XB_XCNT(b.x)], 1u);
;     return b;
; __global__ void __launch_bounds__(NTH, 2) mega_kernel(Params p) {
;   extern __shared__ __attribute__((aligned(16))) char smem[];
;   cg::grid_group grid = cg::this_grid();
;   __shared__ __attribute__((aligned(16))) unsigned xb_st[4];
;   if (threadIdx.x < 4) xb_st[threadIdx.x] = 0u;
;   __syncthreads();
;   const XcdBarrier xb = xcd_barrier_post(p.bar(), (volatile LAS unsigned*)xb_st);
_Z11mega_kernel6Params:
	s_load_dword s3, s[0:1], 0xd8
	s_load_dwordx4 s[20:23], s[0:1], 0xc0
	s_load_dwordx2 s[96:97], s[0:1], 0xd0
	s_mov_b32 s84, s2
	s_add_u32 s2, s0, 0xd0
	v_and_b32_e32 v206, 0x3ff, v0
	s_waitcnt lgkmcnt(0)
	v_writelane_b32 v252, s3, 0
	s_addc_u32 s3, s1, 0
	s_mov_b32 s101, 0
	s_movk_i32 s99, 0xa3f
	v_cmp_gt_u32_e32 vcc, 4, v206
	v_lshlrev_b32_e32 v2, 2, v206
	s_and_saveexec_b64 s[4:5], vcc
	v_mov_b32_e32 v1, 0
	ds_write_b32 v2, v1
	s_or_b64 exec, exec, s[4:5]
	s_waitcnt lgkmcnt(0)
	s_barrier
	s_add_u32 s94, s22, 0x1e6c1000
	s_getreg_b32 s4, hwreg(HW_REG_XCC_ID, 0, 4)
	s_addc_u32 s95, s23, 0
	s_and_b32 s4, s4, 15
	v_writelane_b32 v252, s4, 1
	v_cmp_eq_u32_e64 s[6:7], 0, v206
	s_mov_b64 s[4:5], exec
	s_nop 0
	v_writelane_b32 v252, s6, 2
	s_nop 1
	v_writelane_b32 v252, s7, 3
	s_and_b64 s[6:7], s[4:5], s[6:7]
	s_mov_b64 exec, s[6:7]
	s_cbranch_execz .LBB0_5
	s_mov_b64 s[6:7], exec
	v_mbcnt_lo_u32_b32 v1, s6, 0
	v_mbcnt_hi_u32_b32 v1, s7, v1
	v_cmp_eq_u32_e32 vcc, 0, v1
	s_and_b64 s[8:9], exec, vcc
	s_mov_b64 exec, s[8:9]
	s_cbranch_execz .LBB0_5
	v_readlane_b32 s8, v252, 1
	s_lshl_b32 s8, s8, 8
	s_bcnt1_i32_b64 s6, s[6:7]
	v_mov_b32_e32 v1, s8
	v_mov_b32_e32 v3, s6
	global_atomic_add v1, v3, s[94:95] offset:1024

; DI void prep_weights(const Params& p, char* smem) {
;     ...
;   for (int t0 = blockIdx.x * 2; t0 < TOT; t0 += gridDim.x * 2) {
;     const int t = t0 + half;
;     TJob j{}; j.valid = t < TOT;
.Lprep2_tramp:
	s_mov_b32 s100, s96
	s_addk_i32 s84, 0x4a0
	s_movk_i32 s96, 0x80
	s_movk_i32 s99, 0xfcf
	s_mov_b32 s101, 1
	v_lshlrev_b32_e32 v2, 2, v206
	s_branch .Lprep_entry
.Lprep2_ret:
	s_addk_i32 s84, 0xfb60
	s_mov_b32 s96, s100
	s_mov_b32 s101, 0
